# sgu item gate epilogue (u *= s): 8 u loads + 8 LDS reads per g-block batched, counted waits
# speedup vs baseline: 1.0520x; 1.0022x over previous
.LBB0_433:
	v_ashrrev_i32_e32 v6, 4, v96
	v_ashrrev_i32_e32 v7, 31, v6
	v_lshlrev_b64 v[2:3], 10, v[6:7]
	v_lshl_add_u64 v[10:11], v[0:1], 0, v[2:3]
	v_mad_u64_u32 v[6:7], s[8:9], v6, s42, v[80:81]
	v_mov_b64_e32 v[16:17], v[10:11]
	s_lshl_b32 s2, s42, 4
	s_mov_b64 s[8:9], 0x4000
	global_load_dwordx4 v[164:167], v[10:11], off
	ds_read_b128 v[208:211], v6 offset:35840
	v_lshl_add_u64 v[10:11], v[10:11], 0, s[8:9]
	v_add_u32_e32 v6, s2, v6
	global_load_dwordx4 v[168:171], v[10:11], off
	ds_read_b128 v[212:215], v6 offset:35840
	v_lshl_add_u64 v[10:11], v[10:11], 0, s[8:9]
	v_add_u32_e32 v6, s2, v6
	global_load_dwordx4 v[172:175], v[10:11], off
	ds_read_b128 v[216:219], v6 offset:35840
	v_lshl_add_u64 v[10:11], v[10:11], 0, s[8:9]
	v_add_u32_e32 v6, s2, v6
	global_load_dwordx4 v[176:179], v[10:11], off
	ds_read_b128 v[224:227], v6 offset:35840
	v_lshl_add_u64 v[10:11], v[10:11], 0, s[8:9]
	v_add_u32_e32 v6, s2, v6
	global_load_dwordx4 v[180:183], v[10:11], off
	ds_read_b128 v[228:231], v6 offset:35840
	v_lshl_add_u64 v[10:11], v[10:11], 0, s[8:9]
	v_add_u32_e32 v6, s2, v6
	global_load_dwordx4 v[184:187], v[10:11], off
	ds_read_b128 v[232:235], v6 offset:35840
	v_lshl_add_u64 v[10:11], v[10:11], 0, s[8:9]
	v_add_u32_e32 v6, s2, v6
	global_load_dwordx4 v[188:191], v[10:11], off
	ds_read_b128 v[236:239], v6 offset:35840
	v_lshl_add_u64 v[10:11], v[10:11], 0, s[8:9]
	v_add_u32_e32 v6, s2, v6
	global_load_dwordx4 v[192:195], v[10:11], off
	ds_read_b128 v[244:247], v6 offset:35840
	s_waitcnt vmcnt(7) lgkmcnt(7)
	v_and_b32_e32 v13, 0xffff0000, v164
	v_lshlrev_b32_e32 v12, 16, v164
	v_and_b32_e32 v15, 0xffff0000, v208
	v_lshlrev_b32_e32 v14, 16, v208
	v_pk_mul_f32 v[12:13], v[12:13], v[14:15]
	v_cvt_pk_bf16_f32 v2, v12, v13
	v_and_b32_e32 v13, 0xffff0000, v165
	v_lshlrev_b32_e32 v12, 16, v165
	v_and_b32_e32 v15, 0xffff0000, v209
	v_lshlrev_b32_e32 v14, 16, v209
	v_pk_mul_f32 v[12:13], v[12:13], v[14:15]
	v_cvt_pk_bf16_f32 v3, v12, v13
	v_and_b32_e32 v13, 0xffff0000, v166
	v_lshlrev_b32_e32 v12, 16, v166
	v_and_b32_e32 v15, 0xffff0000, v210
	v_lshlrev_b32_e32 v14, 16, v210
	v_pk_mul_f32 v[12:13], v[12:13], v[14:15]
	v_cvt_pk_bf16_f32 v4, v12, v13
	v_and_b32_e32 v13, 0xffff0000, v167
	v_lshlrev_b32_e32 v12, 16, v167
	v_and_b32_e32 v15, 0xffff0000, v211
	v_lshlrev_b32_e32 v14, 16, v211
	v_pk_mul_f32 v[12:13], v[12:13], v[14:15]
	v_cvt_pk_bf16_f32 v5, v12, v13
	global_store_dwordx4 v[16:17], v[2:5], off
	v_lshl_add_u64 v[16:17], v[16:17], 0, s[8:9]
	s_waitcnt vmcnt(7) lgkmcnt(6)
	v_and_b32_e32 v13, 0xffff0000, v168
	v_lshlrev_b32_e32 v12, 16, v168
	v_and_b32_e32 v15, 0xffff0000, v212
	v_lshlrev_b32_e32 v14, 16, v212
	v_pk_mul_f32 v[12:13], v[12:13], v[14:15]
	v_cvt_pk_bf16_f32 v18, v12, v13
	v_and_b32_e32 v13, 0xffff0000, v169
	v_lshlrev_b32_e32 v12, 16, v169
	v_and_b32_e32 v15, 0xffff0000, v213
	v_lshlrev_b32_e32 v14, 16, v213
	v_pk_mul_f32 v[12:13], v[12:13], v[14:15]
	v_cvt_pk_bf16_f32 v19, v12, v13
	v_and_b32_e32 v13, 0xffff0000, v170
	v_lshlrev_b32_e32 v12, 16, v170
	v_and_b32_e32 v15, 0xffff0000, v214
	v_lshlrev_b32_e32 v14, 16, v214
	v_pk_mul_f32 v[12:13], v[12:13], v[14:15]
	v_cvt_pk_bf16_f32 v20, v12, v13
	v_and_b32_e32 v13, 0xffff0000, v171
	v_lshlrev_b32_e32 v12, 16, v171
	v_and_b32_e32 v15, 0xffff0000, v215
	v_lshlrev_b32_e32 v14, 16, v215
	v_pk_mul_f32 v[12:13], v[12:13], v[14:15]
	v_cvt_pk_bf16_f32 v21, v12, v13
	global_store_dwordx4 v[16:17], v[18:21], off
	v_lshl_add_u64 v[16:17], v[16:17], 0, s[8:9]
	s_waitcnt vmcnt(7) lgkmcnt(5)
	v_and_b32_e32 v13, 0xffff0000, v172
	v_lshlrev_b32_e32 v12, 16, v172
	v_and_b32_e32 v15, 0xffff0000, v216
	v_lshlrev_b32_e32 v14, 16, v216
	v_pk_mul_f32 v[12:13], v[12:13], v[14:15]
	v_cvt_pk_bf16_f32 v2, v12, v13
	v_and_b32_e32 v13, 0xffff0000, v173
	v_lshlrev_b32_e32 v12, 16, v173
	v_and_b32_e32 v15, 0xffff0000, v217
	v_lshlrev_b32_e32 v14, 16, v217
	v_pk_mul_f32 v[12:13], v[12:13], v[14:15]
	v_cvt_pk_bf16_f32 v3, v12, v13
	v_and_b32_e32 v13, 0xffff0000, v174
	v_lshlrev_b32_e32 v12, 16, v174
	v_and_b32_e32 v15, 0xffff0000, v218
	v_lshlrev_b32_e32 v14, 16, v218
	v_pk_mul_f32 v[12:13], v[12:13], v[14:15]
	v_cvt_pk_bf16_f32 v4, v12, v13
	v_and_b32_e32 v13, 0xffff0000, v175
	v_lshlrev_b32_e32 v12, 16, v175
	v_and_b32_e32 v15, 0xffff0000, v219
	v_lshlrev_b32_e32 v14, 16, v219
	v_pk_mul_f32 v[12:13], v[12:13], v[14:15]
	v_cvt_pk_bf16_f32 v5, v12, v13
	global_store_dwordx4 v[16:17], v[2:5], off
	v_lshl_add_u64 v[16:17], v[16:17], 0, s[8:9]
	s_waitcnt vmcnt(7) lgkmcnt(4)
	v_and_b32_e32 v13, 0xffff0000, v176
	v_lshlrev_b32_e32 v12, 16, v176
	v_and_b32_e32 v15, 0xffff0000, v224
	v_lshlrev_b32_e32 v14, 16, v224
	v_pk_mul_f32 v[12:13], v[12:13], v[14:15]
	v_cvt_pk_bf16_f32 v18, v12, v13
	v_and_b32_e32 v13, 0xffff0000, v177
	v_lshlrev_b32_e32 v12, 16, v177
	v_and_b32_e32 v15, 0xffff0000, v225
	v_lshlrev_b32_e32 v14, 16, v225
	v_pk_mul_f32 v[12:13], v[12:13], v[14:15]
	v_cvt_pk_bf16_f32 v19, v12, v13
	v_and_b32_e32 v13, 0xffff0000, v178
	v_lshlrev_b32_e32 v12, 16, v178
	v_and_b32_e32 v15, 0xffff0000, v226
	v_lshlrev_b32_e32 v14, 16, v226
	v_pk_mul_f32 v[12:13], v[12:13], v[14:15]
	v_cvt_pk_bf16_f32 v20, v12, v13
	v_and_b32_e32 v13, 0xffff0000, v179
	v_lshlrev_b32_e32 v12, 16, v179
	v_and_b32_e32 v15, 0xffff0000, v227
	v_lshlrev_b32_e32 v14, 16, v227
	v_pk_mul_f32 v[12:13], v[12:13], v[14:15]
	v_cvt_pk_bf16_f32 v21, v12, v13
	global_store_dwordx4 v[16:17], v[18:21], off
	v_lshl_add_u64 v[16:17], v[16:17], 0, s[8:9]
	s_waitcnt vmcnt(7) lgkmcnt(3)
	v_and_b32_e32 v13, 0xffff0000, v180
	v_lshlrev_b32_e32 v12, 16, v180
	v_and_b32_e32 v15, 0xffff0000, v228
	v_lshlrev_b32_e32 v14, 16, v228
	v_pk_mul_f32 v[12:13], v[12:13], v[14:15]
	v_cvt_pk_bf16_f32 v2, v12, v13
	v_and_b32_e32 v13, 0xffff0000, v181
	v_lshlrev_b32_e32 v12, 16, v181
	v_and_b32_e32 v15, 0xffff0000, v229
	v_lshlrev_b32_e32 v14, 16, v229
	v_pk_mul_f32 v[12:13], v[12:13], v[14:15]
	v_cvt_pk_bf16_f32 v3, v12, v13
	v_and_b32_e32 v13, 0xffff0000, v182
	v_lshlrev_b32_e32 v12, 16, v182
	v_and_b32_e32 v15, 0xffff0000, v230
	v_lshlrev_b32_e32 v14, 16, v230
	v_pk_mul_f32 v[12:13], v[12:13], v[14:15]
	v_cvt_pk_bf16_f32 v4, v12, v13
	v_and_b32_e32 v13, 0xffff0000, v183
	v_lshlrev_b32_e32 v12, 16, v183
	v_and_b32_e32 v15, 0xffff0000, v231
	v_lshlrev_b32_e32 v14, 16, v231
	v_pk_mul_f32 v[12:13], v[12:13], v[14:15]
	v_cvt_pk_bf16_f32 v5, v12, v13
	global_store_dwordx4 v[16:17], v[2:5], off
	v_lshl_add_u64 v[16:17], v[16:17], 0, s[8:9]
	s_waitcnt vmcnt(7) lgkmcnt(2)
	v_and_b32_e32 v13, 0xffff0000, v184
	v_lshlrev_b32_e32 v12, 16, v184
	v_and_b32_e32 v15, 0xffff0000, v232
	v_lshlrev_b32_e32 v14, 16, v232
	v_pk_mul_f32 v[12:13], v[12:13], v[14:15]
	v_cvt_pk_bf16_f32 v18, v12, v13
	v_and_b32_e32 v13, 0xffff0000, v185
	v_lshlrev_b32_e32 v12, 16, v185
	v_and_b32_e32 v15, 0xffff0000, v233
	v_lshlrev_b32_e32 v14, 16, v233
	v_pk_mul_f32 v[12:13], v[12:13], v[14:15]
	v_cvt_pk_bf16_f32 v19, v12, v13
	v_and_b32_e32 v13, 0xffff0000, v186
	v_lshlrev_b32_e32 v12, 16, v186
	v_and_b32_e32 v15, 0xffff0000, v234
	v_lshlrev_b32_e32 v14, 16, v234
	v_pk_mul_f32 v[12:13], v[12:13], v[14:15]
	v_cvt_pk_bf16_f32 v20, v12, v13
	v_and_b32_e32 v13, 0xffff0000, v187
	v_lshlrev_b32_e32 v12, 16, v187
	v_and_b32_e32 v15, 0xffff0000, v235
	v_lshlrev_b32_e32 v14, 16, v235
	v_pk_mul_f32 v[12:13], v[12:13], v[14:15]
	v_cvt_pk_bf16_f32 v21, v12, v13
	global_store_dwordx4 v[16:17], v[18:21], off
	v_lshl_add_u64 v[16:17], v[16:17], 0, s[8:9]
	s_waitcnt vmcnt(7) lgkmcnt(1)
	v_and_b32_e32 v13, 0xffff0000, v188
	v_lshlrev_b32_e32 v12, 16, v188
	v_and_b32_e32 v15, 0xffff0000, v236
	v_lshlrev_b32_e32 v14, 16, v236
	v_pk_mul_f32 v[12:13], v[12:13], v[14:15]
	v_cvt_pk_bf16_f32 v2, v12, v13
	v_and_b32_e32 v13, 0xffff0000, v189
	v_lshlrev_b32_e32 v12, 16, v189
	v_and_b32_e32 v15, 0xffff0000, v237
	v_lshlrev_b32_e32 v14, 16, v237
	v_pk_mul_f32 v[12:13], v[12:13], v[14:15]
	v_cvt_pk_bf16_f32 v3, v12, v13
	v_and_b32_e32 v13, 0xffff0000, v190
	v_lshlrev_b32_e32 v12, 16, v190
	v_and_b32_e32 v15, 0xffff0000, v238
	v_lshlrev_b32_e32 v14, 16, v238
	v_pk_mul_f32 v[12:13], v[12:13], v[14:15]
	v_cvt_pk_bf16_f32 v4, v12, v13
	v_and_b32_e32 v13, 0xffff0000, v191
	v_lshlrev_b32_e32 v12, 16, v191
	v_and_b32_e32 v15, 0xffff0000, v239
	v_lshlrev_b32_e32 v14, 16, v239
	v_pk_mul_f32 v[12:13], v[12:13], v[14:15]
	v_cvt_pk_bf16_f32 v5, v12, v13
	global_store_dwordx4 v[16:17], v[2:5], off
	v_lshl_add_u64 v[16:17], v[16:17], 0, s[8:9]
	s_waitcnt vmcnt(7) lgkmcnt(0)
	v_and_b32_e32 v13, 0xffff0000, v192
	v_lshlrev_b32_e32 v12, 16, v192
	v_and_b32_e32 v15, 0xffff0000, v244
	v_lshlrev_b32_e32 v14, 16, v244
	v_pk_mul_f32 v[12:13], v[12:13], v[14:15]
	v_cvt_pk_bf16_f32 v18, v12, v13
	v_and_b32_e32 v13, 0xffff0000, v193
	v_lshlrev_b32_e32 v12, 16, v193
	v_and_b32_e32 v15, 0xffff0000, v245
	v_lshlrev_b32_e32 v14, 16, v245
	v_pk_mul_f32 v[12:13], v[12:13], v[14:15]
	v_cvt_pk_bf16_f32 v19, v12, v13
	v_and_b32_e32 v13, 0xffff0000, v194
	v_lshlrev_b32_e32 v12, 16, v194
	v_and_b32_e32 v15, 0xffff0000, v246
	v_lshlrev_b32_e32 v14, 16, v246
	v_pk_mul_f32 v[12:13], v[12:13], v[14:15]
	v_cvt_pk_bf16_f32 v20, v12, v13
	v_and_b32_e32 v13, 0xffff0000, v195
	v_lshlrev_b32_e32 v12, 16, v195
	v_and_b32_e32 v15, 0xffff0000, v247
	v_lshlrev_b32_e32 v14, 16, v247
	v_pk_mul_f32 v[12:13], v[12:13], v[14:15]
	v_cvt_pk_bf16_f32 v21, v12, v13
	global_store_dwordx4 v[16:17], v[18:21], off
	s_add_i32 s14, s14, 1
	s_cmp_eq_u32 s14, 4
	s_barrier
	s_cbranch_scc0 .LBB0_432
